# thin_gemm units of the kvq and second gate-up phases run on the workgroups without the extra tile
# speedup vs baseline: 1.0621x; 1.0019x over previous
.LBB0_687:
	s_waitcnt vmcnt(0)
	v_mov_b32_e32 v0, v177
	v_readlane_b32 s0, v254, 0
	s_mov_b32 s99, s29
	s_cmpk_eq_i32 s29, 0x100
	s_cbranch_scc0 .Lthin_nomap
	v_readlane_b32 s98, v255, 30
	s_nop 3
	s_mov_b32 s101, 0
	s_cmp_eq_u32 s98, 11
	s_cselect_b32 s101, 0x80, s101
	s_cmp_eq_u32 s98, 16
	s_cselect_b32 s101, 0x80, s101
	s_sub_u32 s99, 0x100, s101
	s_sub_i32 s0, s0, s101
	s_cmp_lt_i32 s0, 0
	s_cbranch_scc1 .LBB0_718
.Lthin_nomap:
	s_cmp_ge_i32 s0, s20
	v_readfirstlane_b32 s2, v0
	s_cbranch_scc1 .LBB0_718
	v_bfe_u32 v38, v0, 2, 4
	v_and_b32_e32 v43, 15, v0
	v_bfe_u32 v140, v0, 4, 2
	v_lshlrev_b32_e32 v43, 4, v43
	v_lshl_or_b32 v43, v140, 2, v43
	s_lshr_b32 s1, s72, 3
	v_and_b32_e32 v1, 63, v0
	s_ashr_i32 s2, s2, 6
	v_or_b32_e32 v2, 0x2000, v38
	v_readlane_b32 s6, v255, 42
	v_lshl_add_u32 v4, v1, 2, 0
	s_mul_i32 s4, s2, s1
	v_lshrrev_b32_e32 v1, 1, v0
	v_mul_u32_u24_e32 v172, s6, v2
	s_lshl_b32 s15, s2, 11
	v_and_b32_e32 v5, 7, v0
	s_mov_b32 s2, 0x3ffffff0
	v_lshl_add_u64 v[2:3], v[172:173], 1, s[64:65]
	v_and_b32_e32 v172, 3, v0
	v_lshlrev_b32_e32 v172, 4, v172
	v_cmp_gt_i32_e64 s[40:41], s97, v0
	v_ashrrev_i32_e32 v39, 3, v0
	v_and_or_b32 v0, v1, s2, v5
	v_lshlrev_b32_e32 v6, 2, v0
	v_or_b32_e32 v7, 0x2000, v5
	v_mov_b64_e32 v[0:1], s[24:25]
	s_movk_i32 s2, 0x1800
	s_ashr_i32 s5, s4, 31
	v_mad_u64_u32 v[0:1], s[26:27], v7, s2, v[0:1]
	s_lshl_b64 s[10:11], s[4:5], 1
	s_mov_b64 s[26:27], 0x1b819800
	v_lshl_add_u64 v[2:3], v[2:3], 0, s[10:11]
	v_lshl_add_u64 v[10:11], v[0:1], 0, s[26:27]
	v_lshlrev_b32_e32 v0, 11, v7
	v_mov_b32_e32 v1, v173
	v_lshl_add_u64 v[8:9], v[2:3], 0, v[172:173]
	v_lshl_add_u64 v[0:1], s[24:25], 0, v[0:1]
	s_mov_b64 s[26:27], 0x19719800
	v_lshlrev_b32_e32 v2, 12, v5
	v_mov_b32_e32 v3, v173
	v_lshl_add_u64 v[12:13], v[0:1], 0, s[26:27]
	s_waitcnt lgkmcnt(0)
	v_lshl_add_u64 v[2:3], s[42:43], 0, v[2:3]
	s_mov_b64 s[26:27], 0x74c4000
	v_lshl_add_u64 v[14:15], v[2:3], 0, s[26:27]
	s_mov_b64 s[26:27], 0x1a799800
	v_lshl_add_u64 v[16:17], v[0:1], 0, s[26:27]
	s_mov_b64 s[26:27], 0x74cc000
	v_mov_b64_e32 v[0:1], s[82:83]
	s_movk_i32 s2, 0x2c00
	v_lshl_add_u64 v[18:19], v[2:3], 0, s[26:27]
	v_mad_u64_u32 v[20:21], s[26:27], v7, s2, v[0:1]
	v_lshlrev_b32_e32 v0, 13, v7
	v_mov_b32_e32 v1, v173
	s_add_u32 s4, s24, 0xd500000
	v_lshl_add_u64 v[0:1], s[24:25], 0, v[0:1]
	s_mov_b64 s[26:27], 0xd700200
	s_addc_u32 s5, s25, 0
	v_lshl_add_u64 v[22:23], v[0:1], 0, s[26:27]
	v_lshlrev_b32_e32 v0, 13, v5
	v_mov_b32_e32 v1, v173
	s_add_u32 s6, s24, 0xd600100
	v_lshl_add_u64 v[24:25], s[8:9], 0, v[0:1]
	v_lshlrev_b32_e32 v0, 8, v7
	s_addc_u32 s7, s25, 0
	v_lshl_add_u64 v[0:1], s[24:25], 0, v[0:1]
	s_mov_b64 s[8:9], 0x13a00200
	s_movk_i32 s2, 0x2600
	v_lshl_add_u64 v[26:27], v[0:1], 0, s[8:9]
	v_mad_u64_u32 v[28:29], s[8:9], v7, s2, v[20:21]
	s_add_u32 s2, s24, s10
	s_addc_u32 s9, s25, s11
	v_readlane_b32 s10, v255, 38
	v_lshlrev_b32_e32 v0, 8, v39
	v_readlane_b32 s11, v255, 39
	s_add_u32 s8, s2, s10
	s_mov_b32 s73, s31
	v_and_b32_e32 v0, 0x300, v0
	s_addc_u32 s9, s9, s11
	v_add3_u32 v40, 0, v6, v0
	v_add3_u32 v41, 0, v0, v6
	v_lshl_add_u64 v[30:31], s[8:9], 0, v[172:173]
	s_lshl_b64 s[26:27], s[72:73], 1
	s_movk_i32 s73, 0x1000
	s_lshl_b32 s2, s0, 4
	s_lshl_b32 s10, s99, 4
	v_add_u32_e32 v42, s15, v4
	s_branch .LBB0_690
.LBB0_689:
	s_or_b64 exec, exec, s[8:9]
	s_add_i32 s0, s0, s99
	s_add_i32 s2, s2, s10
	s_cmp_ge_i32 s0, s20
	s_barrier
	s_cbranch_scc1 .LBB0_718
